# rnn pass 1 gates: sigmoid argument as one fma with pre-scaled bias (32 VALU ops fewer per unit-thread)
# speedup vs baseline: 1.0024x; 1.0024x over previous
; #define LAS __attribute__((address_space(3)))
; DI float sigm(float x) { return __builtin_amdgcn_rcpf(1.0f + __builtin_amdgcn_exp2f(-x * LOG2E)); }
; #define MFMA32(a, b, c) __builtin_amdgcn_mfma_f32_32x32x16_bf16((a), (b), (c), 0, 0, 0)
; DI void rnn_phase(LAS unsigned char* lds, bf16_t* P, const bf16_t* WaT, const bf16_t* WiT, const float* convw, const float* convb, const float* ba, const float* bi, const float* lam,
;                   f32x2* sums, unsigned* au, bool fin, int bx, int G, int tid, int wid, int lane) {
;     ...
;             f32x16 aR, aI;
; #pragma unroll
;             for (int i = 0; i < 16; ++i) { aR[i] = 0.f; aI[i] = 0.f; }
; #pragma unroll
;             for (int s = 0; s < 4; ++s) {
;                 const bf16x8 af = *(const LAS bf16x8*)(XB + (32 * tt + l32) * 72 + 16 * s + 8 * hl);
;                 const bf16x8 bR = *(const LAS bf16x8*)(WL + (32 * nt + l32) * 72 + 16 * s + 8 * hl);
;                 const bf16x8 bI = *(const LAS bf16x8*)(WL + 64 * 72 + (32 * nt + l32) * 72 + 16 * s + 8 * hl);
;                 aR = MFMA32(af, bR, aR); aI = MFMA32(af, bI, aI);
;             }
;             const int ch = 32 * nt + l32;
;             float At = 1.f, Ht = 0.f;
; #pragma unroll
;             for (int g = 0; g < 4; ++g) {
;                 float A = 1.f, H = 0.f;
; #pragma unroll
;                 for (int q4 = 0; q4 < 4; ++q4) { const int i = 4 * g + q4, tok = 32 * tt + 8 * g + 4 * hl + q4;
;                     const float r = sigm(aR[i] + bac), ig = sigm(aI[i] + bic);
;                     const float a = __builtin_amdgcn_exp2f(k8c * r);
;                     const float uu_ = __builtin_amdgcn_sqrtf(fmaxf(1.0f - a * a, 0.f)) * ig * XC[tok * 64 + ch];
;                     { const h2_t pv = {(_Float16)(1.0f - a), (_Float16)uu_}; au[(rowbase + tok) * D + ch0 + ch] = __builtin_bit_cast(unsigned, pv); }
;                     H = a * H + uu_; A *= a; }
.LBB0_360:
	v_mov_b32_e32 v210, 0xbfb8aa3b
	v_mul_f32_e32 v211, v210, v75
	v_mul_f32_e32 v212, v210, v143
	s_waitcnt lgkmcnt(0)
	s_barrier
	ds_read_b128 v[0:3], v120
	ds_read_b128 v[4:7], v121
	s_ashr_i32 s58, s18, 10
	s_waitcnt lgkmcnt(0)
	v_mfma_f32_32x32x16_bf16 v[16:31], v[0:3], v[4:7], 0
	ds_read_b128 v[4:7], v122
	ds_read_b128 v[150:153], v120 offset:32
	ds_read_b128 v[154:157], v121 offset:32
	s_bfe_u32 s21, s18, 0x60004
	s_ashr_i32 s59, s58, 31
	s_lshl_b64 s[60:61], s[58:59], 13
	s_lshl_b32 s12, s21, 7
	s_or_b32 s60, s60, s12
	s_waitcnt lgkmcnt(0)
	v_mfma_f32_32x32x16_bf16 v[0:15], v[0:3], v[4:7], 0
	s_lshl_b32 s88, s63, 2
	v_lshl_add_u64 v[82:83], v[78:79], 0, s[88:89]
	v_mov_b64_e32 v[208:209], s[60:61]
	v_lshlrev_b64 v[208:209], 12, v[208:209]
	v_lshl_add_u64 v[208:209], v[82:83], 0, v[208:209]
	v_mfma_f32_32x32x16_bf16 v[16:31], v[150:153], v[154:157], v[16:31]
	ds_read_b128 v[154:157], v122 offset:32
	s_waitcnt lgkmcnt(0)
	v_mfma_f32_32x32x16_bf16 v[0:15], v[150:153], v[154:157], v[0:15]
	ds_read_b128 v[150:153], v120 offset:64
	ds_read_b128 v[154:157], v121 offset:64
	s_waitcnt lgkmcnt(0)
	v_mfma_f32_32x32x16_bf16 v[16:31], v[150:153], v[154:157], v[16:31]
	ds_read_b128 v[154:157], v120 offset:96
	ds_read_b128 v[158:161], v121 offset:96
	ds_read_b128 v[172:175], v122 offset:96
	s_waitcnt lgkmcnt(0)
	v_mfma_f32_32x32x16_bf16 v[16:31], v[154:157], v[158:161], v[16:31]
	ds_read_b128 v[158:161], v122 offset:64
	s_waitcnt lgkmcnt(0)
	v_mfma_f32_32x32x16_bf16 v[0:15], v[150:153], v[158:161], v[0:15]
	s_nop 8
	v_fma_f32 v16, v16, v210, v211
	v_exp_f32_e32 v16, v16
	v_fma_f32 v17, v17, v210, v211
	v_exp_f32_e32 v80, v17
	v_add_f32_e32 v16, 1.0, v16
	v_mfma_f32_32x32x16_bf16 v[0:15], v[154:157], v[172:175], v[0:15]
	v_rcp_f32_e32 v16, v16
	v_add_f32_e32 v80, 1.0, v80
	v_rcp_f32_e32 v80, v80
	ds_read_b32 v147, v127
	ds_read_b32 v149, v128
	ds_read_b32 v150, v129
	ds_read_b32 v151, v130
	ds_read_b32 v152, v131
	ds_read_b32 v153, v132
	ds_read_b32 v154, v133
	ds_read_b32 v155, v134
	v_mul_f32_e32 v16, v144, v16
	v_exp_f32_e32 v69, v16
	v_fma_f32 v0, v0, v210, v212
	v_exp_f32_e32 v0, v0
	v_fma_f32 v16, -v69, v69, 1.0
	v_max_f32_e32 v16, 0, v16
	v_sqrt_f32_e32 v145, v16
	v_add_f32_e32 v0, 1.0, v0
	v_rcp_f32_e32 v0, v0
	v_fma_f32 v1, v1, v210, v212
	v_mul_f32_e32 v0, v0, v145
	s_waitcnt lgkmcnt(0)
	v_mul_f32_e32 v145, v147, v0
	v_mul_f32_e32 v0, v144, v80
	v_exp_f32_e32 v80, v0
	v_exp_f32_e32 v147, v1
	v_sub_f32_e32 v146, 1.0, v69
	v_fma_f32 v17, -v80, v80, 1.0
	v_add_f32_e32 v16, 1.0, v147
	v_max_f32_e32 v17, 0, v17
	v_rcp_f32_e32 v16, v16
	v_sqrt_f32_e32 v17, v17
	v_cvt_pk_f16_f32 v146, v146, v145
	v_lshl_add_u64 v[0:1], v[176:177], 0, v[208:209]
	global_store_dword v[0:1], v146, off
	v_fma_f32 v1, v18, v210, v211
	v_mul_f32_e32 v0, v16, v17
	v_exp_f32_e32 v17, v1
	v_fma_f32 v2, v2, v210, v212
	v_exp_f32_e32 v2, v2
	v_add_f32_e32 v17, 1.0, v17
	v_rcp_f32_e32 v17, v17
	v_mul_f32_e32 v16, v149, v0
	v_sub_f32_e32 v0, 1.0, v80
	v_cvt_pk_f16_f32 v18, v0, v16
	v_mul_f32_e32 v17, v144, v17
	v_exp_f32_e32 v17, v17
	v_add_f32_e32 v2, 1.0, v2
	v_fma_f32 v146, -v17, v17, 1.0
	v_max_f32_e32 v146, 0, v146
	v_rcp_f32_e32 v2, v2
	v_sqrt_f32_e32 v146, v146
	v_lshl_add_u64 v[0:1], v[178:179], 0, v[208:209]
	global_store_dword v[0:1], v18, off
	v_fma_f32 v1, v19, v210, v211
	v_mul_f32_e32 v0, v2, v146
	v_exp_f32_e32 v2, v1
	v_fma_f32 v3, v3, v210, v212
	v_fmac_f32_e32 v145, 0, v69
	v_add_f32_e32 v2, 1.0, v2
	v_rcp_f32_e32 v2, v2
	v_fmac_f32_e32 v16, v80, v145
	v_mul_f32_e32 v18, v69, v80
	v_exp_f32_e32 v3, v3
	v_mul_f32_e32 v2, v144, v2
	v_exp_f32_e32 v80, v2
	v_mul_f32_e32 v69, v150, v0
	v_add_f32_e32 v2, 1.0, v3
	v_sub_f32_e32 v0, 1.0, v17
	v_fma_f32 v3, -v80, v80, 1.0
	v_max_f32_e32 v3, 0, v3
	v_cvt_pk_f16_f32 v19, v0, v69
	v_rcp_f32_e32 v2, v2
	v_sqrt_f32_e32 v3, v3
	v_lshl_add_u64 v[0:1], v[180:181], 0, v[208:209]
	global_store_dword v[0:1], v19, off
	v_fmac_f32_e32 v69, v17, v16
	v_mul_f32_e32 v1, v17, v18
	v_fma_f32 v17, v20, v210, v211
	v_mul_f32_e32 v0, v2, v3
	v_mul_f32_e32 v0, v151, v0
	v_sub_f32_e32 v2, 1.0, v80
	v_exp_f32_e32 v17, v17
	v_cvt_pk_f16_f32 v16, v2, v0
	v_lshl_add_u64 v[2:3], v[182:183], 0, v[208:209]
	global_store_dword v[2:3], v16, off
	v_add_f32_e32 v2, 1.0, v17
	v_rcp_f32_e32 v2, v2
	v_fma_f32 v3, v4, v210, v212
	v_exp_f32_e32 v3, v3
	v_mul_f32_e32 v2, v144, v2
	v_exp_f32_e32 v18, v2
	v_fma_f32 v5, v5, v210, v212
	v_add_f32_e32 v2, 1.0, v3
	v_rcp_f32_e32 v4, v2
	v_fma_f32 v2, -v18, v18, 1.0
	v_max_f32_e32 v2, 0, v2
	v_sqrt_f32_e32 v16, v2
	v_fmac_f32_e32 v0, v80, v69
	v_fma_f32 v6, v6, v210, v212
	v_mul_f32_e32 v4, v4, v16
	v_mul_f32_e32 v19, v152, v4
	v_fma_f32 v4, v21, v210, v211
	v_exp_f32_e32 v4, v4
	v_exp_f32_e32 v21, v5
	v_sub_f32_e32 v16, 1.0, v18
	v_cvt_pk_f16_f32 v20, v16, v19
	v_add_f32_e32 v4, 1.0, v4
	v_rcp_f32_e32 v4, v4
	v_exp_f32_e32 v6, v6
	v_mul_f32_e32 v4, v144, v4
	v_exp_f32_e32 v69, v4
	v_add_f32_e32 v16, 1.0, v21
	v_rcp_f32_e32 v16, v16
	v_fma_f32 v17, -v69, v69, 1.0
	v_max_f32_e32 v17, 0, v17
	v_sqrt_f32_e32 v17, v17
	v_lshl_add_u64 v[4:5], v[184:185], 0, v[208:209]
	global_store_dword v[4:5], v20, off
	v_fma_f32 v5, v22, v210, v211
	v_mul_f32_e32 v4, v16, v17
	v_exp_f32_e32 v17, v5
	v_mul_f32_e32 v16, v4, v153
	v_sub_f32_e32 v4, 1.0, v69
	v_cvt_pk_f16_f32 v20, v4, v16
	v_add_f32_e32 v17, 1.0, v17
	v_rcp_f32_e32 v17, v17
	v_add_f32_e32 v6, 1.0, v6
	v_mul_f32_e32 v17, v144, v17
	v_exp_f32_e32 v17, v17
	v_rcp_f32_e32 v6, v6
	v_lshl_add_u64 v[4:5], v[186:187], 0, v[208:209]
	global_store_dword v[4:5], v20, off
	v_fma_f32 v21, -v17, v17, 1.0
	v_max_f32_e32 v21, 0, v21
	v_sqrt_f32_e32 v21, v21
; DI float sigm(float x) { return __builtin_amdgcn_rcpf(1.0f + __builtin_amdgcn_exp2f(-x * LOG2E)); }
; DI void rnn_phase(LAS unsigned char* lds, bf16_t* P, const bf16_t* WaT, const bf16_t* WiT, const float* convw, const float* convb, const float* ba, const float* bi, const float* lam,
;                   f32x2* sums, unsigned* au, bool fin, int bx, int G, int tid, int wid, int lane) {
;     ...
;                 for (int q4 = 0; q4 < 4; ++q4) { const int i = 4 * g + q4, tok = 32 * tt + 8 * g + 4 * hl + q4;
;                     const float r = sigm(aR[i] + bac), ig = sigm(aI[i] + bic);
;                     const float a = __builtin_amdgcn_exp2f(k8c * r);
;                     const float uu_ = __builtin_amdgcn_sqrtf(fmaxf(1.0f - a * a, 0.f)) * ig * XC[tok * 64 + ch];
;                     { const h2_t pv = {(_Float16)(1.0f - a), (_Float16)uu_}; au[(rowbase + tok) * D + ch0 + ch] = __builtin_bit_cast(unsigned, pv); }
;                     H = a * H + uu_; A *= a; }
;                 const float pA = __shfl_xor(A, 32), pH = __shfl_xor(H, 32);
;                 const float fA = hl ? pA : A, fH = hl ? pH : H, sA = hl ? A : pA, sH = hl ? H : pH;
;                 Ht = fA * Ht + fH; At *= fA; Ht = sA * Ht + sH; At *= sA;
;             }
;             if (hl == 0) { SG[tt * 64 + ch] = At; SG[256 + tt * 64 + ch] = Ht; }
	v_fma_f32 v5, v23, v210, v211
	v_fma_f32 v7, v7, v210, v212
	v_mul_f32_e32 v4, v6, v21
	v_exp_f32_e32 v6, v5
	v_exp_f32_e32 v7, v7
	v_fmac_f32_e32 v19, 0, v18
	v_add_f32_e32 v6, 1.0, v6
	v_rcp_f32_e32 v6, v6
	v_fmac_f32_e32 v16, v69, v19
	v_mul_f32_e32 v19, v4, v154
	v_sub_f32_e32 v4, 1.0, v17
	v_mul_f32_e32 v6, v144, v6
	v_exp_f32_e32 v21, v6
	v_add_f32_e32 v6, 1.0, v7
	v_cvt_pk_f16_f32 v20, v4, v19
	v_fma_f32 v7, -v21, v21, 1.0
	v_max_f32_e32 v7, 0, v7
	v_rcp_f32_e32 v6, v6
	v_sqrt_f32_e32 v7, v7
	v_mul_f32_e32 v18, v18, v69
	v_lshl_add_u64 v[4:5], v[188:189], 0, v[208:209]
	global_store_dword v[4:5], v20, off
	v_fmac_f32_e32 v19, v17, v16
	v_mul_f32_e32 v5, v17, v18
	v_fma_f32 v17, v24, v210, v211
	v_mul_f32_e32 v4, v6, v7
	v_mul_f32_e32 v4, v4, v155
	v_sub_f32_e32 v6, 1.0, v21
	v_exp_f32_e32 v17, v17
	v_cvt_pk_f16_f32 v16, v6, v4
	v_lshl_add_u64 v[6:7], v[190:191], 0, v[208:209]
	global_store_dword v[6:7], v16, off
	v_add_f32_e32 v6, 1.0, v17
	v_rcp_f32_e32 v6, v6
	v_fma_f32 v7, v8, v210, v212
	v_exp_f32_e32 v7, v7
	v_mul_f32_e32 v6, v144, v6
	v_exp_f32_e32 v18, v6
	v_mul_f32_e32 v3, v80, v1
	v_add_f32_e32 v6, 1.0, v7
	v_rcp_f32_e32 v8, v6
	v_fma_f32 v6, -v18, v18, 1.0
	v_max_f32_e32 v6, 0, v6
	v_sqrt_f32_e32 v16, v6
	v_fmac_f32_e32 v4, v21, v19
	v_mul_f32_e32 v7, v21, v5
	v_fma_f32 v9, v9, v210, v212
	v_mul_f32_e32 v8, v8, v16
	ds_read_b32 v16, v135
	ds_read_b32 v19, v136
	ds_read_b32 v20, v137
	ds_read_b32 v21, v138
	ds_read_b32 v22, v139
	ds_read_b32 v23, v140
	ds_read_b32 v24, v141
	ds_read_b32 v69, v142
	s_waitcnt lgkmcnt(0)
	v_mul_f32_e32 v80, v8, v16
	v_fma_f32 v8, v25, v210, v211
	v_exp_f32_e32 v8, v8
	v_exp_f32_e32 v145, v9
	v_sub_f32_e32 v16, 1.0, v18
	v_add_f32_e32 v8, 1.0, v8
	v_rcp_f32_e32 v8, v8
	v_cvt_pk_f16_f32 v25, v16, v80
	v_fma_f32 v10, v10, v210, v212
	v_mul_f32_e32 v8, v144, v8
	v_exp_f32_e32 v146, v8
	v_add_f32_e32 v16, 1.0, v145
	v_rcp_f32_e32 v16, v16
	v_fma_f32 v17, -v146, v146, 1.0
	v_max_f32_e32 v17, 0, v17
	v_sqrt_f32_e32 v17, v17
	v_lshl_add_u64 v[8:9], v[192:193], 0, v[208:209]
	global_store_dword v[8:9], v25, off
	v_fma_f32 v9, v26, v210, v211
	v_mul_f32_e32 v8, v16, v17
	v_exp_f32_e32 v17, v9
	v_exp_f32_e32 v10, v10
	v_mul_f32_e32 v16, v8, v19
	v_add_f32_e32 v17, 1.0, v17
	v_rcp_f32_e32 v17, v17
	v_sub_f32_e32 v8, 1.0, v146
	v_cvt_pk_f16_f32 v19, v8, v16
	v_mul_f32_e32 v17, v144, v17
	v_exp_f32_e32 v17, v17
	v_add_f32_e32 v10, 1.0, v10
	v_rcp_f32_e32 v10, v10
	v_fma_f32 v25, -v17, v17, 1.0
	v_max_f32_e32 v25, 0, v25
	v_sqrt_f32_e32 v25, v25
	v_lshl_add_u64 v[8:9], v[194:195], 0, v[208:209]
	global_store_dword v[8:9], v19, off
	v_fma_f32 v9, v27, v210, v211
	v_mul_f32_e32 v8, v10, v25
	v_exp_f32_e32 v10, v9
	v_fma_f32 v11, v11, v210, v212
	v_exp_f32_e32 v11, v11
	v_add_f32_e32 v10, 1.0, v10
	v_rcp_f32_e32 v10, v10
	v_mul_f32_e32 v19, v8, v20
	v_sub_f32_e32 v8, 1.0, v17
	v_cvt_pk_f16_f32 v20, v8, v19
	v_mul_f32_e32 v10, v144, v10
	v_exp_f32_e32 v25, v10
	v_add_f32_e32 v10, 1.0, v11
	v_rcp_f32_e32 v10, v10
	v_fma_f32 v11, -v25, v25, 1.0
	v_max_f32_e32 v11, 0, v11
	v_sqrt_f32_e32 v11, v11
	v_fmac_f32_e32 v80, 0, v18
	v_fmac_f32_e32 v16, v146, v80
	v_mul_f32_e32 v18, v18, v146
	v_lshl_add_u64 v[8:9], v[196:197], 0, v[208:209]
	global_store_dword v[8:9], v20, off
	v_fmac_f32_e32 v19, v17, v16
	v_mul_f32_e32 v9, v17, v18
	v_fma_f32 v17, v28, v210, v211
	v_mul_f32_e32 v8, v10, v11
	v_mul_f32_e32 v8, v8, v21
	v_sub_f32_e32 v10, 1.0, v25
	v_exp_f32_e32 v17, v17
	v_cvt_pk_f16_f32 v16, v10, v8
	v_lshl_add_u64 v[10:11], v[198:199], 0, v[208:209]
	global_store_dword v[10:11], v16, off
	v_add_f32_e32 v10, 1.0, v17
	v_rcp_f32_e32 v10, v10
	v_fma_f32 v11, v12, v210, v212
	v_exp_f32_e32 v11, v11
	v_mul_f32_e32 v10, v144, v10
	v_exp_f32_e32 v18, v10
	v_fmac_f32_e32 v8, v25, v19
	v_add_f32_e32 v10, 1.0, v11
	v_rcp_f32_e32 v12, v10
	v_fma_f32 v10, -v18, v18, 1.0
	v_max_f32_e32 v10, 0, v10
	v_sqrt_f32_e32 v16, v10
	v_fma_f32 v13, v13, v210, v212
	v_exp_f32_e32 v21, v13
	v_mul_f32_e32 v12, v12, v16
	v_mul_f32_e32 v19, v12, v22
	v_fma_f32 v12, v29, v210, v211
	v_exp_f32_e32 v12, v12
	v_sub_f32_e32 v16, 1.0, v18
	v_cvt_pk_f16_f32 v20, v16, v19
	v_add_f32_e32 v12, 1.0, v12
	v_rcp_f32_e32 v12, v12
	v_fmac_f32_e32 v19, 0, v18
	v_fma_f32 v14, v14, v210, v212
	v_mul_f32_e32 v12, v144, v12
	v_exp_f32_e32 v22, v12
	v_add_f32_e32 v16, 1.0, v21
	v_rcp_f32_e32 v16, v16
	v_fma_f32 v17, -v22, v22, 1.0
	v_max_f32_e32 v17, 0, v17
	v_sqrt_f32_e32 v17, v17
	v_lshl_add_u64 v[12:13], v[200:201], 0, v[208:209]
	global_store_dword v[12:13], v20, off
	v_fma_f32 v13, v30, v210, v211
	v_mul_f32_e32 v12, v16, v17
	v_mul_f32_e32 v16, v12, v23
	v_sub_f32_e32 v12, 1.0, v22
	v_exp_f32_e32 v17, v13
	v_cvt_pk_f16_f32 v20, v12, v16
	v_lshl_add_u64 v[12:13], v[202:203], 0, v[208:209]
	v_add_f32_e32 v17, 1.0, v17
	global_store_dword v[12:13], v20, off
	v_fma_f32 v13, v31, v210, v211
	v_rcp_f32_e32 v17, v17
	v_fmac_f32_e32 v16, v22, v19
	v_exp_f32_e32 v19, v13
	v_mul_f32_e32 v17, v144, v17
	v_exp_f32_e32 v17, v17
	v_exp_f32_e32 v14, v14
	v_add_f32_e32 v19, 1.0, v19
	v_rcp_f32_e32 v19, v19
	v_fma_f32 v21, -v17, v17, 1.0
	v_add_f32_e32 v14, 1.0, v14
	v_max_f32_e32 v21, 0, v21
	v_fma_f32 v15, v15, v210, v212
	v_mul_f32_e32 v19, v144, v19
	v_rcp_f32_e32 v14, v14
	v_sqrt_f32_e32 v21, v21
	v_exp_f32_e32 v19, v19
	v_exp_f32_e32 v15, v15
	v_mul_f32_e32 v12, v14, v21
	v_mul_f32_e32 v14, v12, v24
	v_fma_f32 v21, -v19, v19, 1.0
	v_add_f32_e32 v15, 1.0, v15
	v_max_f32_e32 v21, 0, v21
	v_sub_f32_e32 v12, 1.0, v17
	v_rcp_f32_e32 v15, v15
	v_sqrt_f32_e32 v21, v21
	v_cvt_pk_f16_f32 v20, v12, v14
	v_lshl_add_u64 v[12:13], v[204:205], 0, v[208:209]
	v_mul_f32_e32 v18, v18, v22
	global_store_dword v[12:13], v20, off
	v_mul_f32_e32 v12, v15, v21
	v_fmac_f32_e32 v14, v17, v16
	v_mul_f32_e32 v13, v17, v18
	v_mul_f32_e32 v12, v12, v69
	v_sub_f32_e32 v15, 1.0, v19
	v_mul_f32_e32 v11, v25, v9
	v_cvt_pk_f16_f32 v18, v15, v12
	v_fmac_f32_e32 v12, v19, v14
	v_mul_f32_e32 v15, v19, v13
	ds_bpermute_b32 v2, v123, v3
	ds_bpermute_b32 v1, v123, v0
	ds_bpermute_b32 v6, v123, v7
	ds_bpermute_b32 v5, v123, v4
	ds_bpermute_b32 v10, v123, v11
	ds_bpermute_b32 v9, v123, v8
	ds_bpermute_b32 v13, v123, v15
	ds_bpermute_b32 v14, v123, v12
	v_lshl_add_u64 v[16:17], v[206:207], 0, v[208:209]
	global_store_dword v[16:17], v18, off
	s_and_saveexec_b64 s[38:39], s[40:41]
	s_cbranch_execz .LBB0_362
	v_fmac_f32_e32 v0, 0, v3
	s_waitcnt lgkmcnt(0)
	v_mul_f32_e32 v16, v3, v2
	v_fmac_f32_e32 v1, v0, v2
	v_mul_f32_e32 v16, v7, v16
	v_fmac_f32_e32 v4, v7, v1
	v_mul_f32_e32 v16, v16, v6
	v_fmac_f32_e32 v5, v4, v6
	v_mul_f32_e32 v16, v11, v16
	v_fmac_f32_e32 v8, v11, v5
	v_mul_f32_e32 v16, v16, v10
	v_fmac_f32_e32 v9, v8, v10
	v_mul_f32_e32 v16, v15, v16
	v_fmac_f32_e32 v12, v15, v9
	v_mul_f32_e32 v16, v16, v13
	v_fmac_f32_e32 v14, v12, v13
	ds_write2st64_b32 v124, v16, v14 offset1:4
